# packed SwiGLU epilogue + 96 unreachable s_nop after s_branch so later code keeps v43 offsets
# baseline (speedup 1.0000x reference)
.LBB0_1108:
	v_mov_b32_e32 v174, 0xbfb8aa3b
	v_mov_b32_e32 v175, 0xbfb8aa3b
	v_pk_mul_f32 v[152:153], v[126:127], v[174:175]
	v_pk_mul_f32 v[154:155], v[128:129], v[174:175]
	v_pk_mul_f32 v[156:157], v[118:119], v[174:175]
	v_pk_mul_f32 v[158:159], v[120:121], v[174:175]
	v_exp_f32_e32 v152, v152
	v_exp_f32_e32 v153, v153
	v_exp_f32_e32 v154, v154
	v_exp_f32_e32 v155, v155
	v_exp_f32_e32 v156, v156
	v_exp_f32_e32 v157, v157
	v_exp_f32_e32 v158, v158
	v_exp_f32_e32 v159, v159
	v_pk_add_f32 v[152:153], v[152:153], 1.0 op_sel_hi:[1,0]
	v_pk_add_f32 v[154:155], v[154:155], 1.0 op_sel_hi:[1,0]
	v_pk_add_f32 v[156:157], v[156:157], 1.0 op_sel_hi:[1,0]
	v_pk_add_f32 v[158:159], v[158:159], 1.0 op_sel_hi:[1,0]
	v_rcp_f32_e32 v152, v152
	v_rcp_f32_e32 v153, v153
	v_rcp_f32_e32 v154, v154
	v_rcp_f32_e32 v155, v155
	v_rcp_f32_e32 v156, v156
	v_rcp_f32_e32 v157, v157
	v_rcp_f32_e32 v158, v158
	v_rcp_f32_e32 v159, v159
	v_pk_mul_f32 v[152:153], v[126:127], v[152:153]
	v_pk_mul_f32 v[154:155], v[128:129], v[154:155]
	v_pk_mul_f32 v[156:157], v[118:119], v[156:157]
	v_pk_mul_f32 v[158:159], v[120:121], v[158:159]
	v_pk_mul_f32 v[152:153], v[152:153], v[122:123]
	v_pk_mul_f32 v[154:155], v[154:155], v[124:125]
	v_pk_mul_f32 v[156:157], v[156:157], v[114:115]
	v_pk_mul_f32 v[158:159], v[158:159], v[116:117]
	s_nop 0
	v_cvt_pk_bf16_f32 v168, v152, v153
	v_cvt_pk_bf16_f32 v169, v154, v155
	v_cvt_pk_bf16_f32 v170, v156, v157
	v_cvt_pk_bf16_f32 v171, v158, v159
	v_lshl_add_u32 v148, s28, 7, v144
	v_lshl_add_u32 v146, s86, 8, v142
	v_ashrrev_i32_e32 v149, 31, v148
	v_mov_b64_e32 v[140:141], s[8:9]
	v_mad_i64_i32 v[150:151], s[28:29], v146, s73, v[140:141]
	s_andn2_b64 vcc, exec, s[4:5]
	v_lshlrev_b64 v[114:115], 1, v[148:149]
	v_lshl_add_u64 v[120:121], v[150:151], 0, v[114:115]
	global_store_dwordx4 v[120:121], v[168:171], off
	v_pk_mul_f32 v[152:153], v[110:111], v[174:175]
	v_pk_mul_f32 v[154:155], v[112:113], v[174:175]
	v_pk_mul_f32 v[156:157], v[102:103], v[174:175]
	v_pk_mul_f32 v[158:159], v[104:105], v[174:175]
	v_exp_f32_e32 v152, v152
	v_exp_f32_e32 v153, v153
	v_exp_f32_e32 v154, v154
	v_exp_f32_e32 v155, v155
	v_exp_f32_e32 v156, v156
	v_exp_f32_e32 v157, v157
	v_exp_f32_e32 v158, v158
	v_exp_f32_e32 v159, v159
	v_pk_add_f32 v[152:153], v[152:153], 1.0 op_sel_hi:[1,0]
	v_pk_add_f32 v[154:155], v[154:155], 1.0 op_sel_hi:[1,0]
	v_pk_add_f32 v[156:157], v[156:157], 1.0 op_sel_hi:[1,0]
	v_pk_add_f32 v[158:159], v[158:159], 1.0 op_sel_hi:[1,0]
	v_rcp_f32_e32 v152, v152
	v_rcp_f32_e32 v153, v153
	v_rcp_f32_e32 v154, v154
	v_rcp_f32_e32 v155, v155
	v_rcp_f32_e32 v156, v156
	v_rcp_f32_e32 v157, v157
	v_rcp_f32_e32 v158, v158
	v_rcp_f32_e32 v159, v159
	v_pk_mul_f32 v[152:153], v[110:111], v[152:153]
	v_pk_mul_f32 v[154:155], v[112:113], v[154:155]
	v_pk_mul_f32 v[156:157], v[102:103], v[156:157]
	v_pk_mul_f32 v[158:159], v[104:105], v[158:159]
	v_pk_mul_f32 v[152:153], v[152:153], v[106:107]
	v_pk_mul_f32 v[154:155], v[154:155], v[108:109]
	v_pk_mul_f32 v[156:157], v[156:157], v[98:99]
	v_pk_mul_f32 v[158:159], v[158:159], v[100:101]
	s_nop 0
	v_cvt_pk_bf16_f32 v168, v152, v153
	v_cvt_pk_bf16_f32 v169, v154, v155
	v_cvt_pk_bf16_f32 v170, v156, v157
	v_cvt_pk_bf16_f32 v171, v158, v159
	v_or_b32_e32 v116, 16, v146
	v_mad_i64_i32 v[116:117], s[28:29], v116, s73, v[140:141]
	v_lshl_add_u64 v[102:103], v[116:117], 0, v[114:115]
	global_store_dwordx4 v[102:103], v[168:171], off
	v_pk_mul_f32 v[152:153], v[94:95], v[174:175]
	v_pk_mul_f32 v[154:155], v[96:97], v[174:175]
	v_pk_mul_f32 v[156:157], v[86:87], v[174:175]
	v_pk_mul_f32 v[158:159], v[88:89], v[174:175]
	v_exp_f32_e32 v152, v152
	v_exp_f32_e32 v153, v153
	v_exp_f32_e32 v154, v154
	v_exp_f32_e32 v155, v155
	v_exp_f32_e32 v156, v156
	v_exp_f32_e32 v157, v157
	v_exp_f32_e32 v158, v158
	v_exp_f32_e32 v159, v159
	v_pk_add_f32 v[152:153], v[152:153], 1.0 op_sel_hi:[1,0]
	v_pk_add_f32 v[154:155], v[154:155], 1.0 op_sel_hi:[1,0]
	v_pk_add_f32 v[156:157], v[156:157], 1.0 op_sel_hi:[1,0]
	v_pk_add_f32 v[158:159], v[158:159], 1.0 op_sel_hi:[1,0]
	v_rcp_f32_e32 v152, v152
	v_rcp_f32_e32 v153, v153
	v_rcp_f32_e32 v154, v154
	v_rcp_f32_e32 v155, v155
	v_rcp_f32_e32 v156, v156
	v_rcp_f32_e32 v157, v157
	v_rcp_f32_e32 v158, v158
	v_rcp_f32_e32 v159, v159
	v_pk_mul_f32 v[152:153], v[94:95], v[152:153]
	v_pk_mul_f32 v[154:155], v[96:97], v[154:155]
	v_pk_mul_f32 v[156:157], v[86:87], v[156:157]
	v_pk_mul_f32 v[158:159], v[88:89], v[158:159]
	v_pk_mul_f32 v[152:153], v[152:153], v[90:91]
	v_pk_mul_f32 v[154:155], v[154:155], v[92:93]
	v_pk_mul_f32 v[156:157], v[156:157], v[82:83]
	v_pk_mul_f32 v[158:159], v[158:159], v[84:85]
	s_nop 0
	v_cvt_pk_bf16_f32 v168, v152, v153
	v_cvt_pk_bf16_f32 v169, v154, v155
	v_cvt_pk_bf16_f32 v170, v156, v157
	v_cvt_pk_bf16_f32 v171, v158, v159
	v_or_b32_e32 v98, 32, v146
	v_mad_i64_i32 v[98:99], s[28:29], v98, s73, v[140:141]
	v_lshl_add_u64 v[86:87], v[98:99], 0, v[114:115]
	global_store_dwordx4 v[86:87], v[168:171], off
	v_pk_mul_f32 v[152:153], v[78:79], v[174:175]
	v_pk_mul_f32 v[154:155], v[80:81], v[174:175]
	v_pk_mul_f32 v[156:157], v[70:71], v[174:175]
	v_pk_mul_f32 v[158:159], v[72:73], v[174:175]
	v_exp_f32_e32 v152, v152
	v_exp_f32_e32 v153, v153
	v_exp_f32_e32 v154, v154
	v_exp_f32_e32 v155, v155
	v_exp_f32_e32 v156, v156
	v_exp_f32_e32 v157, v157
	v_exp_f32_e32 v158, v158
	v_exp_f32_e32 v159, v159
	v_pk_add_f32 v[152:153], v[152:153], 1.0 op_sel_hi:[1,0]
	v_pk_add_f32 v[154:155], v[154:155], 1.0 op_sel_hi:[1,0]
	v_pk_add_f32 v[156:157], v[156:157], 1.0 op_sel_hi:[1,0]
	v_pk_add_f32 v[158:159], v[158:159], 1.0 op_sel_hi:[1,0]
	v_rcp_f32_e32 v152, v152
	v_rcp_f32_e32 v153, v153
	v_rcp_f32_e32 v154, v154
	v_rcp_f32_e32 v155, v155
	v_rcp_f32_e32 v156, v156
	v_rcp_f32_e32 v157, v157
	v_rcp_f32_e32 v158, v158
	v_rcp_f32_e32 v159, v159
	v_pk_mul_f32 v[152:153], v[78:79], v[152:153]
	v_pk_mul_f32 v[154:155], v[80:81], v[154:155]
	v_pk_mul_f32 v[156:157], v[70:71], v[156:157]
	v_pk_mul_f32 v[158:159], v[72:73], v[158:159]
	v_pk_mul_f32 v[152:153], v[152:153], v[74:75]
	v_pk_mul_f32 v[154:155], v[154:155], v[76:77]
	v_pk_mul_f32 v[156:157], v[156:157], v[66:67]
	v_pk_mul_f32 v[158:159], v[158:159], v[68:69]
	s_nop 0
	v_cvt_pk_bf16_f32 v168, v152, v153
	v_cvt_pk_bf16_f32 v169, v154, v155
	v_cvt_pk_bf16_f32 v170, v156, v157
	v_cvt_pk_bf16_f32 v171, v158, v159
	v_or_b32_e32 v82, 48, v146
	v_mad_i64_i32 v[82:83], s[28:29], v82, s73, v[140:141]
	v_lshl_add_u64 v[70:71], v[82:83], 0, v[114:115]
	global_store_dwordx4 v[70:71], v[168:171], off
	v_pk_mul_f32 v[152:153], v[62:63], v[174:175]
	v_pk_mul_f32 v[154:155], v[64:65], v[174:175]
	v_pk_mul_f32 v[156:157], v[54:55], v[174:175]
	v_pk_mul_f32 v[158:159], v[56:57], v[174:175]
	v_exp_f32_e32 v152, v152
	v_exp_f32_e32 v153, v153
	v_exp_f32_e32 v154, v154
	v_exp_f32_e32 v155, v155
	v_exp_f32_e32 v156, v156
	v_exp_f32_e32 v157, v157
	v_exp_f32_e32 v158, v158
	v_exp_f32_e32 v159, v159
	v_pk_add_f32 v[152:153], v[152:153], 1.0 op_sel_hi:[1,0]
	v_pk_add_f32 v[154:155], v[154:155], 1.0 op_sel_hi:[1,0]
	v_pk_add_f32 v[156:157], v[156:157], 1.0 op_sel_hi:[1,0]
	v_pk_add_f32 v[158:159], v[158:159], 1.0 op_sel_hi:[1,0]
	v_rcp_f32_e32 v152, v152
	v_rcp_f32_e32 v153, v153
	v_rcp_f32_e32 v154, v154
	v_rcp_f32_e32 v155, v155
	v_rcp_f32_e32 v156, v156
	v_rcp_f32_e32 v157, v157
	v_rcp_f32_e32 v158, v158
	v_rcp_f32_e32 v159, v159
	v_pk_mul_f32 v[152:153], v[62:63], v[152:153]
	v_pk_mul_f32 v[154:155], v[64:65], v[154:155]
	v_pk_mul_f32 v[156:157], v[54:55], v[156:157]
	v_pk_mul_f32 v[158:159], v[56:57], v[158:159]
	v_pk_mul_f32 v[152:153], v[152:153], v[58:59]
	v_pk_mul_f32 v[154:155], v[154:155], v[60:61]
	v_pk_mul_f32 v[156:157], v[156:157], v[50:51]
	v_pk_mul_f32 v[158:159], v[158:159], v[52:53]
	s_nop 0
	v_cvt_pk_bf16_f32 v168, v152, v153
	v_cvt_pk_bf16_f32 v169, v154, v155
	v_cvt_pk_bf16_f32 v170, v156, v157
	v_cvt_pk_bf16_f32 v171, v158, v159
	v_add_u32_e32 v66, 0x80, v146
	v_mad_i64_i32 v[66:67], s[28:29], v66, s73, v[140:141]
	v_lshl_add_u64 v[54:55], v[66:67], 0, v[114:115]
	global_store_dwordx4 v[54:55], v[168:171], off
	v_pk_mul_f32 v[152:153], v[46:47], v[174:175]
	v_pk_mul_f32 v[154:155], v[48:49], v[174:175]
	v_pk_mul_f32 v[156:157], v[38:39], v[174:175]
	v_pk_mul_f32 v[158:159], v[40:41], v[174:175]
	v_exp_f32_e32 v152, v152
	v_exp_f32_e32 v153, v153
	v_exp_f32_e32 v154, v154
	v_exp_f32_e32 v155, v155
	v_exp_f32_e32 v156, v156
	v_exp_f32_e32 v157, v157
	v_exp_f32_e32 v158, v158
	v_exp_f32_e32 v159, v159
	v_pk_add_f32 v[152:153], v[152:153], 1.0 op_sel_hi:[1,0]
	v_pk_add_f32 v[154:155], v[154:155], 1.0 op_sel_hi:[1,0]
	v_pk_add_f32 v[156:157], v[156:157], 1.0 op_sel_hi:[1,0]
	v_pk_add_f32 v[158:159], v[158:159], 1.0 op_sel_hi:[1,0]
	v_rcp_f32_e32 v152, v152
	v_rcp_f32_e32 v153, v153
	v_rcp_f32_e32 v154, v154
	v_rcp_f32_e32 v155, v155
	v_rcp_f32_e32 v156, v156
	v_rcp_f32_e32 v157, v157
	v_rcp_f32_e32 v158, v158
	v_rcp_f32_e32 v159, v159
	v_pk_mul_f32 v[152:153], v[46:47], v[152:153]
	v_pk_mul_f32 v[154:155], v[48:49], v[154:155]
	v_pk_mul_f32 v[156:157], v[38:39], v[156:157]
	v_pk_mul_f32 v[158:159], v[40:41], v[158:159]
	v_pk_mul_f32 v[152:153], v[152:153], v[42:43]
	v_pk_mul_f32 v[154:155], v[154:155], v[44:45]
	v_pk_mul_f32 v[156:157], v[156:157], v[34:35]
	v_pk_mul_f32 v[158:159], v[158:159], v[36:37]
	s_nop 0
	v_cvt_pk_bf16_f32 v168, v152, v153
	v_cvt_pk_bf16_f32 v169, v154, v155
	v_cvt_pk_bf16_f32 v170, v156, v157
	v_cvt_pk_bf16_f32 v171, v158, v159
	v_add_u32_e32 v50, 0x90, v146
	v_mad_i64_i32 v[50:51], s[28:29], v50, s73, v[140:141]
	v_lshl_add_u64 v[38:39], v[50:51], 0, v[114:115]
	global_store_dwordx4 v[38:39], v[168:171], off
	v_pk_mul_f32 v[152:153], v[30:31], v[174:175]
	v_pk_mul_f32 v[154:155], v[32:33], v[174:175]
	v_pk_mul_f32 v[156:157], v[22:23], v[174:175]
	v_pk_mul_f32 v[158:159], v[24:25], v[174:175]
	v_exp_f32_e32 v152, v152
	v_exp_f32_e32 v153, v153
	v_exp_f32_e32 v154, v154
	v_exp_f32_e32 v155, v155
	v_exp_f32_e32 v156, v156
	v_exp_f32_e32 v157, v157
	v_exp_f32_e32 v158, v158
	v_exp_f32_e32 v159, v159
	v_pk_add_f32 v[152:153], v[152:153], 1.0 op_sel_hi:[1,0]
	v_pk_add_f32 v[154:155], v[154:155], 1.0 op_sel_hi:[1,0]
	v_pk_add_f32 v[156:157], v[156:157], 1.0 op_sel_hi:[1,0]
	v_pk_add_f32 v[158:159], v[158:159], 1.0 op_sel_hi:[1,0]
	v_rcp_f32_e32 v152, v152
	v_rcp_f32_e32 v153, v153
	v_rcp_f32_e32 v154, v154
	v_rcp_f32_e32 v155, v155
	v_rcp_f32_e32 v156, v156
	v_rcp_f32_e32 v157, v157
	v_rcp_f32_e32 v158, v158
	v_rcp_f32_e32 v159, v159
	v_pk_mul_f32 v[152:153], v[30:31], v[152:153]
	v_pk_mul_f32 v[154:155], v[32:33], v[154:155]
	v_pk_mul_f32 v[156:157], v[22:23], v[156:157]
	v_pk_mul_f32 v[158:159], v[24:25], v[158:159]
	v_pk_mul_f32 v[152:153], v[152:153], v[26:27]
	v_pk_mul_f32 v[154:155], v[154:155], v[28:29]
	v_pk_mul_f32 v[156:157], v[156:157], v[18:19]
	v_pk_mul_f32 v[158:159], v[158:159], v[20:21]
	s_nop 0
	v_cvt_pk_bf16_f32 v168, v152, v153
	v_cvt_pk_bf16_f32 v169, v154, v155
	v_cvt_pk_bf16_f32 v170, v156, v157
	v_cvt_pk_bf16_f32 v171, v158, v159
	v_add_u32_e32 v34, 0xa0, v146
	v_mad_i64_i32 v[34:35], s[28:29], v34, s73, v[140:141]
	v_lshl_add_u64 v[22:23], v[34:35], 0, v[114:115]
	global_store_dwordx4 v[22:23], v[168:171], off
	v_pk_mul_f32 v[152:153], v[14:15], v[174:175]
	v_pk_mul_f32 v[154:155], v[16:17], v[174:175]
	v_pk_mul_f32 v[156:157], v[6:7], v[174:175]
	v_pk_mul_f32 v[158:159], v[8:9], v[174:175]
	v_exp_f32_e32 v152, v152
	v_exp_f32_e32 v153, v153
	v_exp_f32_e32 v154, v154
	v_exp_f32_e32 v155, v155
	v_exp_f32_e32 v156, v156
	v_exp_f32_e32 v157, v157
	v_exp_f32_e32 v158, v158
	v_exp_f32_e32 v159, v159
	v_pk_add_f32 v[152:153], v[152:153], 1.0 op_sel_hi:[1,0]
	v_pk_add_f32 v[154:155], v[154:155], 1.0 op_sel_hi:[1,0]
	v_pk_add_f32 v[156:157], v[156:157], 1.0 op_sel_hi:[1,0]
	v_pk_add_f32 v[158:159], v[158:159], 1.0 op_sel_hi:[1,0]
	v_rcp_f32_e32 v152, v152
	v_rcp_f32_e32 v153, v153
	v_rcp_f32_e32 v154, v154
	v_rcp_f32_e32 v155, v155
	v_rcp_f32_e32 v156, v156
	v_rcp_f32_e32 v157, v157
	v_rcp_f32_e32 v158, v158
	v_rcp_f32_e32 v159, v159
	v_pk_mul_f32 v[152:153], v[14:15], v[152:153]
	v_pk_mul_f32 v[154:155], v[16:17], v[154:155]
	v_pk_mul_f32 v[156:157], v[6:7], v[156:157]
	v_pk_mul_f32 v[158:159], v[8:9], v[158:159]
	v_pk_mul_f32 v[152:153], v[152:153], v[10:11]
	v_pk_mul_f32 v[154:155], v[154:155], v[12:13]
	v_pk_mul_f32 v[156:157], v[156:157], v[2:3]
	v_pk_mul_f32 v[158:159], v[158:159], v[4:5]
	s_nop 0
	v_cvt_pk_bf16_f32 v168, v152, v153
	v_cvt_pk_bf16_f32 v169, v154, v155
	v_cvt_pk_bf16_f32 v170, v156, v157
	v_cvt_pk_bf16_f32 v171, v158, v159
	v_add_u32_e32 v18, 0xb0, v146
	v_mad_i64_i32 v[18:19], s[28:29], v18, s73, v[140:141]
	s_mov_b64 s[28:29], -1
	v_lshl_add_u64 v[6:7], v[18:19], 0, v[114:115]
	global_store_dwordx4 v[6:7], v[168:171], off
	s_cbranch_vccnz .LBB0_1101
	s_andn2_b64 vcc, exec, s[6:7]
	s_cbranch_vccnz .LBB0_1100
	s_barrier
	s_branch .LBB0_1100
	s_nop 0
	s_nop 0
	s_nop 0
	s_nop 0
	s_nop 0
	s_nop 0
	s_nop 0
	s_nop 0
	s_nop 0
	s_nop 0
	s_nop 0
	s_nop 0
	s_nop 0
	s_nop 0
	s_nop 0
	s_nop 0
	s_nop 0
	s_nop 0
	s_nop 0
	s_nop 0
	s_nop 0
	s_nop 0
	s_nop 0
	s_nop 0
	s_nop 0
	s_nop 0
	s_nop 0
	s_nop 0
	s_nop 0
	s_nop 0
	s_nop 0
	s_nop 0
	s_nop 0
	s_nop 0
	s_nop 0
	s_nop 0
	s_nop 0
	s_nop 0
	s_nop 0
	s_nop 0
	s_nop 0
	s_nop 0
	s_nop 0
	s_nop 0
	s_nop 0
	s_nop 0
	s_nop 0
	s_nop 0
	s_nop 0
	s_nop 0
	s_nop 0
	s_nop 0
	s_nop 0
	s_nop 0
	s_nop 0
	s_nop 0
	s_nop 0
	s_nop 0
	s_nop 0
	s_nop 0
	s_nop 0
	s_nop 0
	s_nop 0
	s_nop 0
	s_nop 0
	s_nop 0
	s_nop 0
	s_nop 0
	s_nop 0
	s_nop 0
	s_nop 0
	s_nop 0
	s_nop 0
	s_nop 0
	s_nop 0
	s_nop 0
	s_nop 0
	s_nop 0
	s_nop 0
	s_nop 0
	s_nop 0
	s_nop 0
	s_nop 0
	s_nop 0
	s_nop 0
	s_nop 0
	s_nop 0
	s_nop 0
	s_nop 0
	s_nop 0
	s_nop 0
	s_nop 0
	s_nop 0
	s_nop 0
	s_nop 0
	s_nop 0
